# leading wave half runs the SwiGLU epilogue at raised priority so its next-unit first load segment overlaps the other half's epilogue (P1,P8)
# baseline (speedup 1.0000x reference)
; #define PG8_BAR __builtin_amdgcn_s_barrier()
; template <class Epi, class Sched, bool ALIGN_EPI = false, bool SP2 = false>
; __device__ __forceinline__ void gemm_phase(PG8_LAS unsigned char* lds, const Gemm g, const Sched& S, const Epi& E) {
;     ...
;         if constexpr (ALIGN_EPI) { if (wr == 0) PG8_BAR; }
;         if constexpr (!Epi::AFTER_DRAIN) { E(acc, cur, wr, wc, fr, fq); S.done(cur); }
.LBB0_137:
	s_cmp_eq_u64 s[12:13], 0
	s_cbranch_scc1 .Leprio_p1
	s_setprio 2

; #define PG8_BAR __builtin_amdgcn_s_barrier()
; template <class Epi, class Sched, bool ALIGN_EPI = false, bool SP2 = false>
; __device__ __forceinline__ void gemm_phase(PG8_LAS unsigned char* lds, const Gemm g, const Sched& S, const Epi& E) {
;     ...
;         if (!has_next) break;
; #pragma unroll
;         for (int a = 0; a < 2; ++a)
; #pragma unroll
;             for (int b = 0; b < 2; ++b)
; #pragma unroll
;                 for (int m = 0; m < 4; ++m)
; #pragma unroll
;                     for (int n = 0; n < 2; ++n) acc[a][b][m][n] = (f32x4){0.f, 0.f, 0.f, 0.f};
;         cur = nxt; cA = nA; cB = nB; ++ui;
;         if constexpr (ALIGN_EPI) { if (wr == 1) PG8_BAR; }
.Ljoin_p1:
	s_setprio 0
	s_cbranch_vccnz .LBB0_130
	s_andn2_b64 vcc, exec, s[8:9]
	s_cbranch_vccnz .LBB0_129
	s_barrier
	s_branch .LBB0_129

; #define PG8_BAR __builtin_amdgcn_s_barrier()
; template <class Epi, class Sched, bool ALIGN_EPI = false, bool SP2 = false>
; __device__ __forceinline__ void gemm_phase(PG8_LAS unsigned char* lds, const Gemm g, const Sched& S, const Epi& E) {
;     ...
;         if constexpr (ALIGN_EPI) { if (wr == 0) PG8_BAR; }
;         if constexpr (!Epi::AFTER_DRAIN) { E(acc, cur, wr, wc, fr, fq); S.done(cur); }
.LBB0_1325:
	s_cmp_eq_u64 s[14:15], 0
	s_cbranch_scc1 .Leprio_p8
	s_setprio 2

; #define PG8_BAR __builtin_amdgcn_s_barrier()
; template <class Epi, class Sched, bool ALIGN_EPI = false, bool SP2 = false>
; __device__ __forceinline__ void gemm_phase(PG8_LAS unsigned char* lds, const Gemm g, const Sched& S, const Epi& E) {
;     ...
;         if (!has_next) break;
; #pragma unroll
;         for (int a = 0; a < 2; ++a)
; #pragma unroll
;             for (int b = 0; b < 2; ++b)
; #pragma unroll
;                 for (int m = 0; m < 4; ++m)
; #pragma unroll
;                     for (int n = 0; n < 2; ++n) acc[a][b][m][n] = (f32x4){0.f, 0.f, 0.f, 0.f};
;         cur = nxt; cA = nA; cB = nB; ++ui;
;         if constexpr (ALIGN_EPI) { if (wr == 1) PG8_BAR; }
.Ljoin_p8:
	s_setprio 0
	s_cbranch_vccnz .LBB0_1318
	s_andn2_b64 vcc, exec, s[4:5]
	s_cbranch_vccnz .LBB0_1317
	s_barrier
	s_branch .LBB0_1317
